# ATTN softmax: xor-32/16 butterfly steps via v_permlane32/16_swap instead of ds_bpermute (bit-identical)
# speedup vs baseline: 1.0120x; 1.0010x over previous
; DI void attn_item(const P& p, int b, int kvh, int quad4, char* smem, const AttnPre& pre) {
;     ...
;   float pr[4][4];
; #pragma unroll
;   for (int h = 0; h < 4; ++h) {
;     float m = -INFINITY;
; #pragma unroll
;     for (int j = 0; j < 4; ++j) { pr[h][j] = L[h * 256 + lane + 64 * j]; m = fmaxf(m, pr[h][j]); }
; #pragma unroll
;     for (int off = 32; off >= 1; off >>= 1) m = fmaxf(m, __shfl_xor(m, off));
;     float sum = 0.f;
; #pragma unroll
;     for (int j = 0; j < 4; ++j) { pr[h][j] = __expf(pr[h][j] - m); sum += pr[h][j]; }
; #pragma unroll
;     for (int off = 32; off >= 1; off >>= 1) sum += __shfl_xor(sum, off);
.LBB0_345:
	s_or_b64 exec, exec, s[6:7]
	s_nop 3
	v_mbcnt_hi_u32_b32 v20, -1, v222
	v_and_b32_e32 v16, 64, v20
	v_add_u32_e32 v21, 64, v16
	ds_read2st64_b32 v[16:17], v106 offset1:1
	ds_read2st64_b32 v[18:19], v106 offset0:2 offset1:3
	ds_read2st64_b32 v[26:27], v106 offset0:6 offset1:7
	ds_read2st64_b32 v[42:43], v106 offset0:14 offset1:15
	v_xor_b32_e32 v23, 32, v20
	s_mov_b32 s6, 0xff800000
	v_cmp_lt_i32_e32 vcc, v23, v21
	s_waitcnt lgkmcnt(3)
	v_max3_f32 v22, v16, s6, v17
	s_waitcnt lgkmcnt(2)
	v_max3_f32 v22, v22, v18, v19
	v_cndmask_b32_e32 v23, v20, v23, vcc
	v_lshlrev_b32_e32 v84, 2, v23
	v_mov_b32_e32 v23, v22
	s_nop 1
	v_permlane32_swap_b32_e32 v23, v22
	v_lshlrev_b32_e32 v192, 3, v105
	ds_read2st64_b32 v[40:41], v106 offset0:12 offset1:13
	s_waitcnt lgkmcnt(1)
	v_max_f32_e32 v23, v23, v23
	v_max_f32_e32 v22, v22, v23
	v_xor_b32_e32 v23, 16, v20
	v_cmp_lt_i32_e32 vcc, v23, v21
	s_nop 1
	v_cndmask_b32_e32 v23, v20, v23, vcc
	v_lshlrev_b32_e32 v85, 2, v23
	v_mov_b32_e32 v23, v22
	s_nop 1
	v_permlane16_swap_b32_e32 v23, v22
	s_waitcnt lgkmcnt(0)
	v_max_f32_e32 v23, v23, v23
	v_max_f32_e32 v22, v22, v23
	v_xor_b32_e32 v23, 8, v20
	v_cmp_lt_i32_e32 vcc, v23, v21
	s_nop 1
	v_cndmask_b32_e32 v23, v20, v23, vcc
	v_lshlrev_b32_e32 v39, 2, v23
	s_nop 1
	v_mov_b32_dpp v23, v22 row_ror:8 row_mask:0xf bank_mask:0xf
	s_waitcnt lgkmcnt(0)
	v_max_f32_e32 v23, v23, v23
	v_max_f32_e32 v22, v22, v23
	v_xor_b32_e32 v23, 4, v20
	v_cmp_lt_i32_e32 vcc, v23, v21
	s_nop 1
	v_cndmask_b32_e32 v23, v20, v23, vcc
	v_lshlrev_b32_e32 v38, 2, v23
	s_nop 1
	v_mov_b32_dpp v23, v22 row_ror:4 row_mask:0xf bank_mask:0xf
	s_waitcnt lgkmcnt(0)
	v_max_f32_e32 v23, v23, v23
	v_max_f32_e32 v22, v22, v23
	v_xor_b32_e32 v23, 2, v20
	v_cmp_lt_i32_e32 vcc, v23, v21
	s_nop 1
	v_cndmask_b32_e32 v23, v20, v23, vcc
	v_lshlrev_b32_e32 v37, 2, v23
	s_nop 1
	v_mov_b32_dpp v23, v22 row_ror:2 row_mask:0xf bank_mask:0xf
	s_waitcnt lgkmcnt(0)
	v_max_f32_e32 v23, v23, v23
	v_max_f32_e32 v22, v22, v23
	v_xor_b32_e32 v23, 1, v20
	v_cmp_lt_i32_e32 vcc, v23, v21
	s_nop 1
	v_cndmask_b32_e32 v20, v20, v23, vcc
	v_lshlrev_b32_e32 v36, 2, v20
	s_nop 1
	v_mov_b32_dpp v20, v22 row_ror:1 row_mask:0xf bank_mask:0xf
	s_waitcnt lgkmcnt(0)
	v_max_f32_e32 v20, v20, v20
	v_max_f32_e32 v20, v22, v20
	v_sub_f32_e32 v17, v17, v20
	v_mul_f32_e32 v17, 0x3fb8aa3b, v17
	v_exp_f32_e32 v24, v17
	v_sub_f32_e32 v17, v18, v20
	v_mul_f32_e32 v17, 0x3fb8aa3b, v17
	v_exp_f32_e32 v22, v17
	v_sub_f32_e32 v17, v19, v20
	ds_read2st64_b32 v[18:19], v106 offset0:4 offset1:5
	v_mul_f32_e32 v17, 0x3fb8aa3b, v17
	v_sub_f32_e32 v16, v16, v20
	v_exp_f32_e32 v20, v17
	v_mul_f32_e32 v16, 0x3fb8aa3b, v16
	s_waitcnt lgkmcnt(0)
	v_max3_f32 v17, v18, s6, v19
	v_max3_f32 v17, v17, v26, v27
	v_mov_b32_e32 v21, v17
	s_nop 1
	v_permlane32_swap_b32_e32 v21, v17
	v_exp_f32_e32 v16, v16
	s_waitcnt lgkmcnt(0)
	v_max_f32_e32 v21, v21, v21
	v_max_f32_e32 v17, v17, v21
	v_mov_b32_e32 v21, v17
	s_nop 1
	v_permlane16_swap_b32_e32 v21, v17
	s_waitcnt lgkmcnt(0)
	v_max_f32_e32 v21, v21, v21
	v_max_f32_e32 v17, v17, v21
	s_nop 1
	v_mov_b32_dpp v21, v17 row_ror:8 row_mask:0xf bank_mask:0xf
	s_waitcnt lgkmcnt(0)
	v_max_f32_e32 v21, v21, v21
	v_max_f32_e32 v17, v17, v21
	s_nop 1
	v_mov_b32_dpp v21, v17 row_ror:4 row_mask:0xf bank_mask:0xf
	s_waitcnt lgkmcnt(0)
	v_max_f32_e32 v21, v21, v21
	v_max_f32_e32 v17, v17, v21
	s_nop 1
	v_mov_b32_dpp v21, v17 row_ror:2 row_mask:0xf bank_mask:0xf
	s_waitcnt lgkmcnt(0)
	v_max_f32_e32 v21, v21, v21
	v_max_f32_e32 v17, v17, v21
	s_nop 1
	v_mov_b32_dpp v21, v17 row_ror:1 row_mask:0xf bank_mask:0xf
	s_waitcnt lgkmcnt(0)
	v_max_f32_e32 v21, v21, v21
	v_max_f32_e32 v21, v17, v21
	v_sub_f32_e32 v17, v18, v21
	v_sub_f32_e32 v18, v19, v21
	v_mul_f32_e32 v18, 0x3fb8aa3b, v18
	v_exp_f32_e32 v25, v18
	v_sub_f32_e32 v18, v26, v21
	v_mul_f32_e32 v18, 0x3fb8aa3b, v18
	v_exp_f32_e32 v23, v18
	v_sub_f32_e32 v18, v27, v21
	v_mul_f32_e32 v18, 0x3fb8aa3b, v18
	v_exp_f32_e32 v21, v18
	ds_read2st64_b32 v[18:19], v106 offset0:8 offset1:9
	ds_read2st64_b32 v[26:27], v106 offset0:10 offset1:11
	v_mul_f32_e32 v17, 0x3fb8aa3b, v17
	v_exp_f32_e32 v17, v17
	s_waitcnt lgkmcnt(1)
	v_max3_f32 v28, v18, s6, v19
	s_waitcnt lgkmcnt(0)
	v_max3_f32 v28, v28, v26, v27
	v_mov_b32_e32 v29, v28
	s_nop 1
	v_permlane32_swap_b32_e32 v29, v28
	v_pk_add_f32 v[32:33], v[16:17], 0 op_sel_hi:[1,0]
	s_waitcnt lgkmcnt(0)
	v_max_f32_e32 v29, v29, v29
	v_max_f32_e32 v28, v28, v29
	v_mov_b32_e32 v29, v28
	s_nop 1
	v_permlane16_swap_b32_e32 v29, v28
	v_pk_add_f32 v[32:33], v[24:25], v[32:33]
	s_waitcnt lgkmcnt(0)
	v_max_f32_e32 v29, v29, v29
	v_max_f32_e32 v28, v28, v29
	s_nop 1
	v_mov_b32_dpp v29, v28 row_ror:8 row_mask:0xf bank_mask:0xf
	v_pk_add_f32 v[32:33], v[22:23], v[32:33]
	s_waitcnt lgkmcnt(0)
	v_max_f32_e32 v29, v29, v29
	v_max_f32_e32 v28, v28, v29
	s_nop 1
	v_mov_b32_dpp v29, v28 row_ror:4 row_mask:0xf bank_mask:0xf
	v_pk_add_f32 v[32:33], v[20:21], v[32:33]
	s_waitcnt lgkmcnt(0)
	v_max_f32_e32 v29, v29, v29
	v_max_f32_e32 v28, v28, v29
	s_nop 1
	v_mov_b32_dpp v29, v28 row_ror:2 row_mask:0xf bank_mask:0xf
	s_waitcnt lgkmcnt(0)
	v_max_f32_e32 v29, v29, v29
	v_max_f32_e32 v28, v28, v29
	s_nop 1
	v_mov_b32_dpp v29, v28 row_ror:1 row_mask:0xf bank_mask:0xf
	s_waitcnt lgkmcnt(0)
	v_max_f32_e32 v29, v29, v29
	v_max_f32_e32 v29, v28, v29
	v_sub_f32_e32 v19, v19, v29
	v_mul_f32_e32 v19, 0x3fb8aa3b, v19
	v_exp_f32_e32 v30, v19
	v_sub_f32_e32 v19, v26, v29
	v_mul_f32_e32 v19, 0x3fb8aa3b, v19
	v_exp_f32_e32 v28, v19
	v_sub_f32_e32 v19, v27, v29
	v_mul_f32_e32 v19, 0x3fb8aa3b, v19
	v_exp_f32_e32 v26, v19
	v_max3_f32 v19, v40, s6, v41
	v_max3_f32 v19, v19, v42, v43
	v_mov_b32_e32 v27, v19
	s_nop 1
	v_permlane32_swap_b32_e32 v27, v19
	v_sub_f32_e32 v18, v18, v29
	v_mul_f32_e32 v18, 0x3fb8aa3b, v18
	v_exp_f32_e32 v18, v18
	s_waitcnt lgkmcnt(0)
; DI void attn_item(const P& p, int b, int kvh, int quad4, char* smem, const AttnPre& pre) {
;     ...
;   for (int h = 0; h < 4; ++h) {
;     float m = -INFINITY;
; #pragma unroll
;     for (int j = 0; j < 4; ++j) { pr[h][j] = L[h * 256 + lane + 64 * j]; m = fmaxf(m, pr[h][j]); }
; #pragma unroll
;     for (int off = 32; off >= 1; off >>= 1) m = fmaxf(m, __shfl_xor(m, off));
;     float sum = 0.f;
; #pragma unroll
;     for (int j = 0; j < 4; ++j) { pr[h][j] = __expf(pr[h][j] - m); sum += pr[h][j]; }
; #pragma unroll
;     for (int off = 32; off >= 1; off >>= 1) sum += __shfl_xor(sum, off);
;     const float inv = 1.f / sum;
; #pragma unroll
;     for (int j = 0; j < 4; ++j) pr[h][j] *= inv;
;   }
;   __builtin_amdgcn_wave_barrier();
; #pragma unroll
;   for (int j = 0; j < 4; ++j) *(float4*)(L + (lane + 64 * j) * 4) = make_float4(pr[0][j], pr[1][j], pr[2][j], pr[3][j]);
;   __builtin_amdgcn_wave_barrier();
;   float o[4][8];
; #pragma unroll
;   for (int h = 0; h < 4; ++h)
; #pragma unroll
;     for (int e = 0; e < 8; ++e) o[h][e] = 0.f;
;   const unsigned char* vb = p.v8 + ((size_t)b * SEQ) * 256 + kvh * 128 + r * 8;
	v_max_f32_e32 v27, v27, v27
	v_max_f32_e32 v19, v19, v27
	v_mov_b32_e32 v27, v19
	s_nop 1
	v_permlane16_swap_b32_e32 v27, v19
	s_waitcnt lgkmcnt(0)
	v_max_f32_e32 v27, v27, v27
	v_max_f32_e32 v19, v19, v27
	s_nop 1
	v_mov_b32_dpp v27, v19 row_ror:8 row_mask:0xf bank_mask:0xf
	s_waitcnt lgkmcnt(0)
	v_max_f32_e32 v27, v27, v27
	v_max_f32_e32 v19, v19, v27
	s_nop 1
	v_mov_b32_dpp v27, v19 row_ror:4 row_mask:0xf bank_mask:0xf
	s_waitcnt lgkmcnt(0)
	v_max_f32_e32 v27, v27, v27
	v_max_f32_e32 v19, v19, v27
	s_nop 1
	v_mov_b32_dpp v27, v19 row_ror:2 row_mask:0xf bank_mask:0xf
	s_waitcnt lgkmcnt(0)
	v_max_f32_e32 v27, v27, v27
	v_max_f32_e32 v19, v19, v27
	s_nop 1
	v_mov_b32_dpp v27, v19 row_ror:1 row_mask:0xf bank_mask:0xf
	s_waitcnt lgkmcnt(0)
	v_max_f32_e32 v27, v27, v27
	v_max_f32_e32 v27, v19, v27
	v_sub_f32_e32 v19, v40, v27
	v_sub_f32_e32 v29, v41, v27
	v_mov_b32_e32 v40, v32
	v_mov_b32_e32 v41, v33
	s_nop 1
	v_permlane32_swap_b32_e32 v40, v32
	v_permlane32_swap_b32_e32 v41, v33
	v_mul_f32_e32 v29, 0x3fb8aa3b, v29
	v_exp_f32_e32 v31, v29
	v_sub_f32_e32 v29, v42, v27
	v_sub_f32_e32 v27, v43, v27
	s_waitcnt lgkmcnt(0)
	v_pk_add_f32 v[32:33], v[32:33], v[40:41]
	v_mov_b32_e32 v40, v32
	v_mov_b32_e32 v41, v33
	s_nop 1
	v_permlane16_swap_b32_e32 v40, v32
	v_permlane16_swap_b32_e32 v41, v33
	v_mul_f32_e32 v19, 0x3fb8aa3b, v19
	v_exp_f32_e32 v19, v19
	v_mul_f32_e32 v29, 0x3fb8aa3b, v29
	v_exp_f32_e32 v29, v29
	s_waitcnt lgkmcnt(0)
	v_pk_add_f32 v[32:33], v[32:33], v[40:41]
	s_nop 1
	v_mov_b32_dpp v40, v32 row_ror:8 row_mask:0xf bank_mask:0xf
	s_nop 1
	v_mov_b32_dpp v41, v33 row_ror:8 row_mask:0xf bank_mask:0xf
	v_mul_f32_e32 v27, 0x3fb8aa3b, v27
	v_exp_f32_e32 v27, v27
	v_pk_add_f32 v[34:35], v[18:19], 0 op_sel_hi:[1,0]
	s_waitcnt lgkmcnt(0)
	v_pk_add_f32 v[32:33], v[32:33], v[40:41]
	s_nop 1
	v_mov_b32_dpp v40, v32 row_ror:4 row_mask:0xf bank_mask:0xf
	s_nop 1
	v_mov_b32_dpp v41, v33 row_ror:4 row_mask:0xf bank_mask:0xf
	v_pk_add_f32 v[34:35], v[30:31], v[34:35]
	s_waitcnt lgkmcnt(0)
	v_pk_add_f32 v[32:33], v[32:33], v[40:41]
	s_nop 1
	v_mov_b32_dpp v40, v32 row_ror:2 row_mask:0xf bank_mask:0xf
	s_nop 1
	v_mov_b32_dpp v41, v33 row_ror:2 row_mask:0xf bank_mask:0xf
	v_pk_add_f32 v[34:35], v[28:29], v[34:35]
	s_waitcnt lgkmcnt(0)
	v_pk_add_f32 v[32:33], v[32:33], v[40:41]
	s_nop 1
	v_mov_b32_dpp v40, v32 row_ror:1 row_mask:0xf bank_mask:0xf
	s_nop 1
	v_mov_b32_dpp v41, v33 row_ror:1 row_mask:0xf bank_mask:0xf
	v_pk_add_f32 v[34:35], v[26:27], v[34:35]
	s_waitcnt lgkmcnt(0)
	v_pk_add_f32 v[32:33], v[32:33], v[40:41]
	s_nop 0
	v_div_scale_f32 v40, s[6:7], v33, v33, 1.0
	v_rcp_f32_e32 v41, v40
	s_nop 0
	v_fma_f32 v42, -v40, v41, 1.0
	v_fmac_f32_e32 v41, v42, v41
	v_div_scale_f32 v42, vcc, 1.0, v33, 1.0
	v_mul_f32_e32 v43, v42, v41
	v_fma_f32 v44, -v40, v43, v42
	v_fmac_f32_e32 v43, v44, v41
	v_fma_f32 v40, -v40, v43, v42
	v_div_fmas_f32 v40, v40, v41, v43
	v_div_fixup_f32 v33, v40, v33, 1.0
	v_div_scale_f32 v40, s[6:7], v32, v32, 1.0
	v_rcp_f32_e32 v41, v40
	s_nop 0
	v_fma_f32 v42, -v40, v41, 1.0
	v_fmac_f32_e32 v41, v42, v41
	v_div_scale_f32 v42, vcc, 1.0, v32, 1.0
	v_mul_f32_e32 v43, v42, v41
	v_fma_f32 v44, -v40, v43, v42
	v_fmac_f32_e32 v43, v44, v41
	v_fma_f32 v40, -v40, v43, v42
	v_div_fmas_f32 v40, v40, v41, v43
	v_div_fixup_f32 v32, v40, v32, 1.0
	v_mov_b32_e32 v40, v34
	v_mov_b32_e32 v41, v35
	s_nop 1
	v_permlane32_swap_b32_e32 v40, v34
	v_permlane32_swap_b32_e32 v41, v35
	v_pk_mul_f32 v[16:17], v[16:17], v[32:33]
	s_waitcnt lgkmcnt(0)
	v_pk_add_f32 v[34:35], v[34:35], v[40:41]
	v_mov_b32_e32 v40, v34
	v_mov_b32_e32 v41, v35
	s_nop 1
	v_permlane16_swap_b32_e32 v40, v34
	v_permlane16_swap_b32_e32 v41, v35
	s_waitcnt lgkmcnt(0)
	v_pk_add_f32 v[34:35], v[34:35], v[40:41]
	s_nop 1
	v_mov_b32_dpp v40, v34 row_ror:8 row_mask:0xf bank_mask:0xf
	s_nop 1
	v_mov_b32_dpp v41, v35 row_ror:8 row_mask:0xf bank_mask:0xf
	s_waitcnt lgkmcnt(0)
	v_pk_add_f32 v[34:35], v[34:35], v[40:41]
	s_nop 1
	v_mov_b32_dpp v40, v34 row_ror:4 row_mask:0xf bank_mask:0xf
	s_nop 1
	v_mov_b32_dpp v41, v35 row_ror:4 row_mask:0xf bank_mask:0xf
	s_waitcnt lgkmcnt(0)
	v_pk_add_f32 v[34:35], v[34:35], v[40:41]
	s_nop 1
	v_mov_b32_dpp v38, v34 row_ror:2 row_mask:0xf bank_mask:0xf
	s_nop 1
	v_mov_b32_dpp v39, v35 row_ror:2 row_mask:0xf bank_mask:0xf
	s_waitcnt lgkmcnt(0)
	v_pk_add_f32 v[34:35], v[34:35], v[38:39]
	s_nop 1
	v_mov_b32_dpp v38, v34 row_ror:1 row_mask:0xf bank_mask:0xf
	s_nop 1
	v_mov_b32_dpp v39, v35 row_ror:1 row_mask:0xf bank_mask:0xf
	s_waitcnt lgkmcnt(0)
	v_pk_add_f32 v[34:35], v[34:35], v[38:39]
	s_nop 0
	v_div_scale_f32 v36, s[6:7], v35, v35, 1.0
	v_rcp_f32_e32 v37, v36
	s_nop 0
	v_fma_f32 v38, -v36, v37, 1.0
	v_fmac_f32_e32 v37, v38, v37
	v_div_scale_f32 v38, vcc, 1.0, v35, 1.0
	v_mul_f32_e32 v39, v38, v37
	v_fma_f32 v40, -v36, v39, v38
	v_fmac_f32_e32 v39, v40, v37
	v_fma_f32 v36, -v36, v39, v38
	v_div_fmas_f32 v36, v36, v37, v39
	v_div_fixup_f32 v35, v36, v35, 1.0
	v_div_scale_f32 v36, s[6:7], v34, v34, 1.0
	v_rcp_f32_e32 v37, v36
	v_readlane_b32 s6, v250, 15
	s_add_u32 s6, s6, s10
	v_readlane_b32 s7, v250, 16
	v_fma_f32 v38, -v36, v37, 1.0
	v_fmac_f32_e32 v37, v38, v37
	v_div_scale_f32 v38, vcc, 1.0, v34, 1.0
	v_mul_f32_e32 v39, v38, v37
	v_fma_f32 v40, -v36, v39, v38
	v_fmac_f32_e32 v39, v40, v37
	v_fma_f32 v36, -v36, v39, v38
	v_div_fmas_f32 v36, v36, v37, v39
	v_div_fixup_f32 v34, v36, v34, 1.0
	v_pk_mul_f32 v[18:19], v[18:19], v[34:35]
	ds_write_b128 v104, v[16:19]
	v_pk_mul_f32 v[16:17], v[24:25], v[32:33]
	v_pk_mul_f32 v[18:19], v[30:31], v[34:35]
	ds_write_b128 v104, v[16:19] offset:1024
	v_pk_mul_f32 v[16:17], v[22:23], v[32:33]
	v_pk_mul_f32 v[18:19], v[28:29], v[34:35]
	ds_write_b128 v104, v[16:19] offset:2048
	v_pk_mul_f32 v[16:17], v[20:21], v[32:33]
	v_pk_mul_f32 v[18:19], v[26:27], v[34:35]
	ds_write_b128 v104, v[16:19] offset:3072
	s_addc_u32 s7, s7, s11
	v_lshrrev_b32_e32 v16, 2, v102
	v_lshl_add_u64 v[24:25], s[6:7], 0, v[192:193]
	v_and_b32_e32 v16, 12, v16
	s_add_i32 s6, 0, 0x1000
	v_add3_u32 v86, v103, v16, s6
	v_and_b32_e32 v16, 48, v102
	v_add3_u32 v87, v103, v16, 0
	v_mov_b32_e32 v16, 0
	s_movk_i32 s6, 0xffc0
	v_mov_b32_e32 v17, v16
	v_mov_b32_e32 v20, v16
	v_mov_b32_e32 v21, v16
	v_mov_b32_e32 v28, v16
	v_mov_b32_e32 v29, v16
	v_mov_b32_e32 v36, v16
	v_mov_b32_e32 v37, v16
	v_mov_b32_e32 v18, v16
	v_mov_b32_e32 v19, v16
	v_mov_b32_e32 v22, v16
	v_mov_b32_e32 v23, v16
	v_mov_b32_e32 v32, v16
	v_mov_b32_e32 v33, v16
	v_mov_b32_e32 v40, v16
	v_mov_b32_e32 v41, v16
	v_mov_b32_e32 v26, v16
	v_mov_b32_e32 v27, v16
	v_mov_b32_e32 v34, v16
	v_mov_b32_e32 v35, v16
	v_mov_b32_e32 v42, v16
	v_mov_b32_e32 v43, v16
	v_mov_b32_e32 v46, v16
	v_mov_b32_e32 v47, v16
	v_mov_b32_e32 v30, v16
	v_mov_b32_e32 v31, v16
	v_mov_b32_e32 v38, v16
	v_mov_b32_e32 v39, v16
	v_mov_b32_e32 v44, v16
	v_mov_b32_e32 v45, v16
	v_mov_b32_e32 v48, v16
	v_mov_b32_e32 v49, v16
